# FF1 GEMM k-loop: SB(0,1) LDS-DMA stage op moved from the 6-piece load segment to the next 2-piece segment (4/4 balance for that half), counted wait 8->6
# baseline (speedup 1.0000x reference)
.LBB0_1451:
	s_add_u32 s30, s28, 0xfff80080
	s_addc_u32 s31, s29, -1
	s_add_i32 s55, 0, 0x10000
	s_cmp_eq_u32 s54, 28
	s_cselect_b32 s35, s15, s31
	s_cselect_b32 s34, s50, s30
	s_cselect_b32 s31, s13, s53
	s_cselect_b32 s30, s51, s52
	s_add_i32 s58, 0, 0x14000
	v_add_u32_e32 v154, s55, v139
	v_add_u32_e32 v158, s58, v139
	ds_read_b128 v[142:145], v154
	ds_read_b128 v[146:149], v154 offset:1024
	ds_read_b128 v[150:153], v154 offset:2048
	ds_read_b128 v[154:157], v154 offset:3072
	ds_read_b128 v[172:175], v158
	ds_read_b128 v[176:179], v158 offset:1024
	ds_read_b128 v[180:183], v158 offset:2048
	ds_read_b128 v[184:187], v158 offset:3072
	v_lshl_add_u64 v[158:159], s[28:29], 0, v[134:135]
	s_add_i32 m0, s27, 0xc000
	ds_read_b128 v[196:199], v141
	ds_read_b128 v[200:203], v141 offset:1024
	ds_read_b128 v[204:207], v141 offset:2048
	ds_read_b128 v[208:211], v141 offset:3072
	ds_read_b128 v[212:215], v141 offset:4096
	ds_read_b128 v[234:237], v141 offset:5120
	ds_read_b128 v[238:241], v141 offset:6144
	ds_read_b128 v[242:245], v141 offset:7168
	global_load_lds_dwordx4 v[158:159], off
	v_lshl_add_u64 v[158:159], s[28:29], 0, v[136:137]
	s_add_i32 m0, s27, 0xe000
	s_nop 0
	global_load_lds_dwordx4 v[158:159], off
	s_waitcnt vmcnt(8)
	s_waitcnt lgkmcnt(0)
	s_barrier
	s_setprio 1
	s_waitcnt lgkmcnt(0)
	v_mfma_f32_16x16x32_bf16 v[124:127], v[142:145], v[196:199], v[124:127]
	v_mfma_f32_16x16x32_bf16 v[120:123], v[150:153], v[196:199], v[120:123]
	v_mfma_f32_16x16x32_bf16 v[108:111], v[142:145], v[204:207], v[108:111]
	v_mfma_f32_16x16x32_bf16 v[104:107], v[150:153], v[204:207], v[104:107]
	v_mfma_f32_16x16x32_bf16 v[92:95], v[142:145], v[212:215], v[92:95]
	v_mfma_f32_16x16x32_bf16 v[88:91], v[150:153], v[212:215], v[88:91]
	v_mfma_f32_16x16x32_bf16 v[76:79], v[142:145], v[238:241], v[76:79]
	v_mfma_f32_16x16x32_bf16 v[72:75], v[150:153], v[238:241], v[72:75]
	v_mfma_f32_16x16x32_bf16 v[124:127], v[146:149], v[200:203], v[124:127]
	v_mfma_f32_16x16x32_bf16 v[120:123], v[154:157], v[200:203], v[120:123]
	v_mfma_f32_16x16x32_bf16 v[108:111], v[146:149], v[208:211], v[108:111]
	v_mfma_f32_16x16x32_bf16 v[104:107], v[154:157], v[208:211], v[104:107]
	v_mfma_f32_16x16x32_bf16 v[92:95], v[146:149], v[234:237], v[92:95]
	v_mfma_f32_16x16x32_bf16 v[88:91], v[154:157], v[234:237], v[88:91]
	v_mfma_f32_16x16x32_bf16 v[76:79], v[146:149], v[242:245], v[76:79]
	v_mfma_f32_16x16x32_bf16 v[72:75], v[154:157], v[242:245], v[72:75]
	s_setprio 0
	s_setprio 1
	v_mfma_f32_16x16x32_bf16 v[116:119], v[172:175], v[196:199], v[116:119]
	v_mfma_f32_16x16x32_bf16 v[112:115], v[180:183], v[196:199], v[112:115]
	v_mfma_f32_16x16x32_bf16 v[100:103], v[172:175], v[204:207], v[100:103]
	v_mfma_f32_16x16x32_bf16 v[96:99], v[180:183], v[204:207], v[96:99]
	v_mfma_f32_16x16x32_bf16 v[84:87], v[172:175], v[212:215], v[84:87]
	v_mfma_f32_16x16x32_bf16 v[80:83], v[180:183], v[212:215], v[80:83]
	v_mfma_f32_16x16x32_bf16 v[68:71], v[172:175], v[238:241], v[68:71]
	v_mfma_f32_16x16x32_bf16 v[64:67], v[180:183], v[238:241], v[64:67]
	v_mfma_f32_16x16x32_bf16 v[116:119], v[176:179], v[200:203], v[116:119]
	v_mfma_f32_16x16x32_bf16 v[112:115], v[184:187], v[200:203], v[112:115]
	v_mfma_f32_16x16x32_bf16 v[100:103], v[176:179], v[208:211], v[100:103]
	v_mfma_f32_16x16x32_bf16 v[96:99], v[184:187], v[208:211], v[96:99]
	v_mfma_f32_16x16x32_bf16 v[84:87], v[176:179], v[234:237], v[84:87]
	v_mfma_f32_16x16x32_bf16 v[80:83], v[184:187], v[234:237], v[80:83]
	v_mfma_f32_16x16x32_bf16 v[68:71], v[176:179], v[242:245], v[68:71]
	v_mfma_f32_16x16x32_bf16 v[64:67], v[184:187], v[242:245], v[64:67]
	s_setprio 0
	s_barrier
	s_add_i32 s55, s55, s39
	v_lshl_add_u64 v[158:159], s[30:31], 0, v[160:161]
	s_mov_b32 m0, s55
	ds_read_b128 v[196:199], v141 offset:16384
	ds_read_b128 v[200:203], v141 offset:17408
	ds_read_b128 v[204:207], v141 offset:18432
	ds_read_b128 v[208:211], v141 offset:19456
	ds_read_b128 v[212:215], v141 offset:20480
	ds_read_b128 v[234:237], v141 offset:21504
	ds_read_b128 v[238:241], v141 offset:22528
	ds_read_b128 v[242:245], v141 offset:23552
	global_load_lds_dwordx4 v[158:159], off
	s_add_i32 m0, s55, 0x2000
	s_add_u32 s56, s30, 0x80000
	v_lshl_add_u64 v[188:189], s[30:31], 0, v[128:129]
	s_addc_u32 s57, s31, 0
	s_add_i32 s55, s58, s39
	global_load_lds_dwordx4 v[188:189], off
	v_lshl_add_u64 v[246:247], s[34:35], 0, v[130:131]
	v_lshl_add_u64 v[216:217], s[34:35], 0, v[132:133]
	s_mov_b32 m0, s27
	s_nop 0
	global_load_lds_dwordx4 v[216:217], off
	s_mov_b32 m0, s43
	s_nop 0
	global_load_lds_dwordx4 v[246:247], off
	s_waitcnt vmcnt(6)
	s_waitcnt lgkmcnt(0)
	s_barrier
	s_setprio 1
	s_waitcnt lgkmcnt(0)
	v_mfma_f32_16x16x32_bf16 v[60:63], v[142:145], v[196:199], v[60:63]
	v_mfma_f32_16x16x32_bf16 v[56:59], v[150:153], v[196:199], v[56:59]
	v_mfma_f32_16x16x32_bf16 v[44:47], v[142:145], v[204:207], v[44:47]
	v_mfma_f32_16x16x32_bf16 v[40:43], v[150:153], v[204:207], v[40:43]
	v_mfma_f32_16x16x32_bf16 v[28:31], v[142:145], v[212:215], v[28:31]
	v_mfma_f32_16x16x32_bf16 v[24:27], v[150:153], v[212:215], v[24:27]
	v_mfma_f32_16x16x32_bf16 v[12:15], v[142:145], v[238:241], v[12:15]
	v_mfma_f32_16x16x32_bf16 v[8:11], v[150:153], v[238:241], v[8:11]
	v_mfma_f32_16x16x32_bf16 v[60:63], v[146:149], v[200:203], v[60:63]
	v_mfma_f32_16x16x32_bf16 v[56:59], v[154:157], v[200:203], v[56:59]
	v_mfma_f32_16x16x32_bf16 v[44:47], v[146:149], v[208:211], v[44:47]
	v_mfma_f32_16x16x32_bf16 v[40:43], v[154:157], v[208:211], v[40:43]
	v_mfma_f32_16x16x32_bf16 v[28:31], v[146:149], v[234:237], v[28:31]
	v_mfma_f32_16x16x32_bf16 v[24:27], v[154:157], v[234:237], v[24:27]
	v_mfma_f32_16x16x32_bf16 v[12:15], v[146:149], v[242:245], v[12:15]
	v_mfma_f32_16x16x32_bf16 v[8:11], v[154:157], v[242:245], v[8:11]
	s_setprio 0
	s_setprio 1
	v_mfma_f32_16x16x32_bf16 v[52:55], v[172:175], v[196:199], v[52:55]
	v_mfma_f32_16x16x32_bf16 v[48:51], v[180:183], v[196:199], v[48:51]
	v_mfma_f32_16x16x32_bf16 v[36:39], v[172:175], v[204:207], v[36:39]
	v_mfma_f32_16x16x32_bf16 v[32:35], v[180:183], v[204:207], v[32:35]
	v_mfma_f32_16x16x32_bf16 v[20:23], v[172:175], v[212:215], v[20:23]
	v_mfma_f32_16x16x32_bf16 v[16:19], v[180:183], v[212:215], v[16:19]
	v_mfma_f32_16x16x32_bf16 v[4:7], v[172:175], v[238:241], v[4:7]
	v_mfma_f32_16x16x32_bf16 v[0:3], v[180:183], v[238:241], v[0:3]
	v_mfma_f32_16x16x32_bf16 v[52:55], v[176:179], v[200:203], v[52:55]
	v_mfma_f32_16x16x32_bf16 v[48:51], v[184:187], v[200:203], v[48:51]
	v_mfma_f32_16x16x32_bf16 v[36:39], v[176:179], v[208:211], v[36:39]
	v_mfma_f32_16x16x32_bf16 v[32:35], v[184:187], v[208:211], v[32:35]
	v_mfma_f32_16x16x32_bf16 v[20:23], v[176:179], v[234:237], v[20:23]
	v_mfma_f32_16x16x32_bf16 v[16:19], v[184:187], v[234:237], v[16:19]
	v_mfma_f32_16x16x32_bf16 v[4:7], v[176:179], v[242:245], v[4:7]
	v_mfma_f32_16x16x32_bf16 v[0:3], v[184:187], v[242:245], v[0:3]
	s_setprio 0
	s_barrier
	s_add_i32 s55, 0, 0x18000
	s_add_i32 s56, 0, 0x1c000
	v_add_u32_e32 v154, s55, v139
	v_add_u32_e32 v162, s56, v139
	ds_read_b128 v[142:145], v154
	ds_read_b128 v[146:149], v154 offset:1024
	ds_read_b128 v[150:153], v154 offset:2048
	ds_read_b128 v[154:157], v154 offset:3072
	ds_read_b128 v[172:175], v162
	ds_read_b128 v[176:179], v162 offset:1024
	ds_read_b128 v[180:183], v162 offset:2048
	ds_read_b128 v[184:187], v162 offset:3072
	s_add_u32 s34, s34, 0x80000
	s_addc_u32 s35, s35, 0
	s_add_u32 vcc_lo, s30, 0x80000
	s_addc_u32 vcc_hi, s31, 0
	s_add_i32 m0, s39, 0x14000
	s_nop 0
	global_load_lds_dwordx4 v160, vcc
	s_add_i32 m0, s39, 0x16000
	s_nop 0
	global_load_lds_dwordx4 v128, vcc
	s_mov_b32 m0, s44
	v_lshl_add_u64 v[248:249], s[34:35], 0, v[132:133]
	ds_read_b128 v[196:199], v141 offset:32768
	ds_read_b128 v[200:203], v141 offset:33792
	ds_read_b128 v[204:207], v141 offset:34816
	ds_read_b128 v[208:211], v141 offset:35840
	ds_read_b128 v[212:215], v141 offset:36864
	ds_read_b128 v[234:237], v141 offset:37888
	ds_read_b128 v[238:241], v141 offset:38912
	ds_read_b128 v[242:245], v141 offset:39936
	global_load_lds_dwordx4 v[248:249], off
	v_lshl_add_u64 v[248:249], s[34:35], 0, v[130:131]
	s_mov_b32 m0, s45
	s_nop 0
	global_load_lds_dwordx4 v[248:249], off
	s_waitcnt vmcnt(8)
	s_waitcnt lgkmcnt(0)
	s_barrier
	s_setprio 1
	s_waitcnt lgkmcnt(0)
	v_mfma_f32_16x16x32_bf16 v[124:127], v[142:145], v[196:199], v[124:127]
	v_mfma_f32_16x16x32_bf16 v[120:123], v[150:153], v[196:199], v[120:123]
	v_mfma_f32_16x16x32_bf16 v[108:111], v[142:145], v[204:207], v[108:111]
	v_mfma_f32_16x16x32_bf16 v[104:107], v[150:153], v[204:207], v[104:107]
	v_mfma_f32_16x16x32_bf16 v[92:95], v[142:145], v[212:215], v[92:95]
	v_mfma_f32_16x16x32_bf16 v[88:91], v[150:153], v[212:215], v[88:91]
	v_mfma_f32_16x16x32_bf16 v[76:79], v[142:145], v[238:241], v[76:79]
	v_mfma_f32_16x16x32_bf16 v[72:75], v[150:153], v[238:241], v[72:75]
	v_mfma_f32_16x16x32_bf16 v[124:127], v[146:149], v[200:203], v[124:127]
	v_mfma_f32_16x16x32_bf16 v[120:123], v[154:157], v[200:203], v[120:123]
	v_mfma_f32_16x16x32_bf16 v[108:111], v[146:149], v[208:211], v[108:111]
	v_mfma_f32_16x16x32_bf16 v[104:107], v[154:157], v[208:211], v[104:107]
	v_mfma_f32_16x16x32_bf16 v[92:95], v[146:149], v[234:237], v[92:95]
	v_mfma_f32_16x16x32_bf16 v[88:91], v[154:157], v[234:237], v[88:91]
	v_mfma_f32_16x16x32_bf16 v[76:79], v[146:149], v[242:245], v[76:79]
	v_mfma_f32_16x16x32_bf16 v[72:75], v[154:157], v[242:245], v[72:75]
	s_setprio 0
	s_setprio 1
	v_mfma_f32_16x16x32_bf16 v[116:119], v[172:175], v[196:199], v[116:119]
	v_mfma_f32_16x16x32_bf16 v[112:115], v[180:183], v[196:199], v[112:115]
	v_mfma_f32_16x16x32_bf16 v[100:103], v[172:175], v[204:207], v[100:103]
	v_mfma_f32_16x16x32_bf16 v[96:99], v[180:183], v[204:207], v[96:99]
	v_mfma_f32_16x16x32_bf16 v[84:87], v[172:175], v[212:215], v[84:87]
	v_mfma_f32_16x16x32_bf16 v[80:83], v[180:183], v[212:215], v[80:83]
	v_mfma_f32_16x16x32_bf16 v[68:71], v[172:175], v[238:241], v[68:71]
	v_mfma_f32_16x16x32_bf16 v[64:67], v[180:183], v[238:241], v[64:67]
	v_mfma_f32_16x16x32_bf16 v[116:119], v[176:179], v[200:203], v[116:119]
	v_mfma_f32_16x16x32_bf16 v[112:115], v[184:187], v[200:203], v[112:115]
	v_mfma_f32_16x16x32_bf16 v[100:103], v[176:179], v[208:211], v[100:103]
	v_mfma_f32_16x16x32_bf16 v[96:99], v[184:187], v[208:211], v[96:99]
	v_mfma_f32_16x16x32_bf16 v[84:87], v[176:179], v[234:237], v[84:87]
	v_mfma_f32_16x16x32_bf16 v[80:83], v[184:187], v[234:237], v[80:83]
	v_mfma_f32_16x16x32_bf16 v[68:71], v[176:179], v[242:245], v[68:71]
	v_mfma_f32_16x16x32_bf16 v[64:67], v[184:187], v[242:245], v[64:67]
	s_setprio 0
	s_barrier
	s_add_i32 s34, s55, s39
	v_lshl_add_u64 v[158:159], v[158:159], 0, s[20:21]
	s_mov_b32 m0, s34
	ds_read_b128 v[196:199], v141 offset:49152
	ds_read_b128 v[200:203], v141 offset:50176
	ds_read_b128 v[204:207], v141 offset:51200
	ds_read_b128 v[208:211], v141 offset:52224
	ds_read_b128 v[212:215], v141 offset:53248
	ds_read_b128 v[234:237], v141 offset:54272
	ds_read_b128 v[238:241], v141 offset:55296
	ds_read_b128 v[242:245], v141 offset:56320
	global_load_lds_dwordx4 v[158:159], off
	s_add_i32 m0, s34, 0x2000
	s_add_u32 s30, s30, 0x80080
	v_lshl_add_u64 v[158:159], v[188:189], 0, s[20:21]
	s_addc_u32 s31, s31, 0
	s_add_i32 s34, s56, s39
	global_load_lds_dwordx4 v[158:159], off
	v_lshl_add_u64 v[158:159], s[30:31], 0, v[160:161]
	s_mov_b32 m0, s34
	s_nop 0
	global_load_lds_dwordx4 v[158:159], off
	v_lshl_add_u64 v[158:159], s[30:31], 0, v[128:129]
	s_add_i32 m0, s34, 0x2000
	s_nop 0
	global_load_lds_dwordx4 v[158:159], off
	v_lshl_add_u64 v[158:159], v[216:217], 0, s[20:21]
	s_mov_b32 m0, s46
	s_nop 0
	global_load_lds_dwordx4 v[158:159], off
	v_lshl_add_u64 v[158:159], v[246:247], 0, s[20:21]
	s_mov_b32 m0, s47
	s_nop 0
	global_load_lds_dwordx4 v[158:159], off
	s_waitcnt vmcnt(8)
	s_waitcnt lgkmcnt(0)
	s_barrier
	s_setprio 1
	s_waitcnt lgkmcnt(0)
	v_mfma_f32_16x16x32_bf16 v[60:63], v[142:145], v[196:199], v[60:63]
	v_mfma_f32_16x16x32_bf16 v[56:59], v[150:153], v[196:199], v[56:59]
	v_mfma_f32_16x16x32_bf16 v[44:47], v[142:145], v[204:207], v[44:47]
	v_mfma_f32_16x16x32_bf16 v[40:43], v[150:153], v[204:207], v[40:43]
	v_mfma_f32_16x16x32_bf16 v[28:31], v[142:145], v[212:215], v[28:31]
	v_mfma_f32_16x16x32_bf16 v[24:27], v[150:153], v[212:215], v[24:27]
	v_mfma_f32_16x16x32_bf16 v[12:15], v[142:145], v[238:241], v[12:15]
	v_mfma_f32_16x16x32_bf16 v[8:11], v[150:153], v[238:241], v[8:11]
	v_mfma_f32_16x16x32_bf16 v[60:63], v[146:149], v[200:203], v[60:63]
	v_mfma_f32_16x16x32_bf16 v[56:59], v[154:157], v[200:203], v[56:59]
	v_mfma_f32_16x16x32_bf16 v[44:47], v[146:149], v[208:211], v[44:47]
	v_mfma_f32_16x16x32_bf16 v[40:43], v[154:157], v[208:211], v[40:43]
	v_mfma_f32_16x16x32_bf16 v[28:31], v[146:149], v[234:237], v[28:31]
	v_mfma_f32_16x16x32_bf16 v[24:27], v[154:157], v[234:237], v[24:27]
	v_mfma_f32_16x16x32_bf16 v[12:15], v[146:149], v[242:245], v[12:15]
	v_mfma_f32_16x16x32_bf16 v[8:11], v[154:157], v[242:245], v[8:11]
	s_setprio 0
	s_setprio 1
	v_mfma_f32_16x16x32_bf16 v[52:55], v[172:175], v[196:199], v[52:55]
	v_mfma_f32_16x16x32_bf16 v[48:51], v[180:183], v[196:199], v[48:51]
	v_mfma_f32_16x16x32_bf16 v[36:39], v[172:175], v[204:207], v[36:39]
	v_mfma_f32_16x16x32_bf16 v[32:35], v[180:183], v[204:207], v[32:35]
	v_mfma_f32_16x16x32_bf16 v[20:23], v[172:175], v[212:215], v[20:23]
	v_mfma_f32_16x16x32_bf16 v[16:19], v[180:183], v[212:215], v[16:19]
	v_mfma_f32_16x16x32_bf16 v[4:7], v[172:175], v[238:241], v[4:7]
	v_mfma_f32_16x16x32_bf16 v[0:3], v[180:183], v[238:241], v[0:3]
	v_mfma_f32_16x16x32_bf16 v[52:55], v[176:179], v[200:203], v[52:55]
	v_mfma_f32_16x16x32_bf16 v[48:51], v[184:187], v[200:203], v[48:51]
	v_mfma_f32_16x16x32_bf16 v[36:39], v[176:179], v[208:211], v[36:39]
	v_mfma_f32_16x16x32_bf16 v[32:35], v[184:187], v[208:211], v[32:35]
	v_mfma_f32_16x16x32_bf16 v[20:23], v[176:179], v[234:237], v[20:23]
	v_mfma_f32_16x16x32_bf16 v[16:19], v[184:187], v[234:237], v[16:19]
	v_mfma_f32_16x16x32_bf16 v[4:7], v[176:179], v[242:245], v[4:7]
	v_mfma_f32_16x16x32_bf16 v[0:3], v[184:187], v[242:245], v[0:3]
	s_setprio 0
	s_barrier
	s_add_i32 s54, s54, 2
	s_add_u32 s28, s28, 0x100
	s_addc_u32 s29, s29, 0
	s_add_u32 s52, s52, 0x100
	s_addc_u32 s53, s53, 0
	s_cmp_gt_u32 s54, 29
	s_cbranch_scc0 .LBB0_1451
	s_and_b64 vcc, exec, s[10:11]
	s_cbranch_vccz .LBB0_1454
	s_barrier
